# EpiResid epilogues (P3,P9,P12) restructured: 16 base loads in flight per wave instead of 2-4
# speedup vs baseline: 1.0068x; 1.0068x over previous
;     __device__ __forceinline__ void operator()(const f32x4 (&acc)[2][2][4][2], const pg8::Unit& u, int wr, int wc, int fr, int fq) const {
;         const int row0 = u.pm * 256 + wr * 64 + fr; const float* gp = gate + (size_t)(u.pm >> 5) * NMOD;
; #pragma unroll
;         for (int bj = 0; bj < 2; ++bj) {
;             const int col = u.pn * 256 + bj * 128 + wc * 32 + 8 * fq;
;             const f32x4 g0 = *(const f32x4*)(gp + col) * coef, g1 = *(const f32x4*)(gp + col + 4) * coef;
; #pragma unroll
;             for (int ai = 0; ai < 2; ++ai)
; #pragma unroll
;                 for (int m = 0; m < 4; ++m) {
;                     const size_t off = (size_t)(row0 + ai * 128 + m * 16) * DM + col;
;                     const f32x4 x0 = *(const f32x4*)(base + off), x1 = *(const f32x4*)(base + off + 4);
;                     *(f32x4*)(out + off) = x0 + g0 * acc[ai][bj][m][0]; *(f32x4*)(out + off + 4) = x1 + g1 * acc[ai][bj][m][1];
;                     if (m & 1) asm volatile("" ::: "memory");
;                 }
;         }
;     }
.LBB0_235:
	v_lshl_add_u32 v240, s70, 8, v160
	v_lshl_add_u32 v241, s71, 8, v162
	v_lshlrev_b32_e32 v240, 10, v240
	v_add_lshl_u32 v240, v240, v241, 2
	v_lshlrev_b32_e32 v241, 2, v241
	s_ashr_i32 s98, s70, 5
	s_mul_i32 s98, s98, 0x9000
	s_add_u32 s98, s44, s98
	s_addc_u32 s99, s45, 0
	global_load_dwordx4 v[144:147], v241, s[98:99]
	global_load_dwordx4 v[148:151], v241, s[98:99] offset:16
	s_add_u32 s100, s36, 0x0
	s_addc_u32 s101, s37, 0
	global_load_dwordx4 v[172:175], v240, s[100:101]
	global_load_dwordx4 v[176:179], v240, s[100:101] offset:16
	s_add_u32 s100, s36, 0x10000
	s_addc_u32 s101, s37, 0
	global_load_dwordx4 v[180:183], v240, s[100:101]
	global_load_dwordx4 v[184:187], v240, s[100:101] offset:16
	s_add_u32 s100, s36, 0x20000
	s_addc_u32 s101, s37, 0
	global_load_dwordx4 v[188:191], v240, s[100:101]
	global_load_dwordx4 v[192:195], v240, s[100:101] offset:16
	s_add_u32 s100, s36, 0x30000
	s_addc_u32 s101, s37, 0
	global_load_dwordx4 v[196:199], v240, s[100:101]
	global_load_dwordx4 v[200:203], v240, s[100:101] offset:16
	s_add_u32 s100, s36, 0x80000
	s_addc_u32 s101, s37, 0
	global_load_dwordx4 v[208:211], v240, s[100:101]
	global_load_dwordx4 v[212:215], v240, s[100:101] offset:16
	s_add_u32 s100, s36, 0x90000
	s_addc_u32 s101, s37, 0
	global_load_dwordx4 v[216:219], v240, s[100:101]
	global_load_dwordx4 v[220:223], v240, s[100:101] offset:16
	s_add_u32 s100, s36, 0xa0000
	s_addc_u32 s101, s37, 0
	global_load_dwordx4 v[224:227], v240, s[100:101]
	global_load_dwordx4 v[228:231], v240, s[100:101] offset:16
	s_add_u32 s100, s36, 0xb0000
	s_addc_u32 s101, s37, 0
	global_load_dwordx4 v[232:235], v240, s[100:101]
	global_load_dwordx4 v[236:239], v240, s[100:101] offset:16
	s_waitcnt vmcnt(16)
	v_pk_mul_f32 v[144:145], v[144:145], 0.5 op_sel_hi:[1,0]
	v_pk_mul_f32 v[146:147], v[146:147], 0.5 op_sel_hi:[1,0]
	v_pk_mul_f32 v[148:149], v[148:149], 0.5 op_sel_hi:[1,0]
	v_pk_mul_f32 v[150:151], v[150:151], 0.5 op_sel_hi:[1,0]
	s_waitcnt vmcnt(14)
	v_pk_fma_f32 v[124:125], v[124:125], v[144:145], v[172:173]
	v_pk_fma_f32 v[126:127], v[126:127], v[146:147], v[174:175]
	v_pk_fma_f32 v[120:121], v[120:121], v[148:149], v[176:177]
	v_pk_fma_f32 v[122:123], v[122:123], v[150:151], v[178:179]
	s_add_u32 s98, s90, 0x0
	s_addc_u32 s99, s91, 0
	global_store_dwordx4 v240, v[124:127], s[98:99]
	global_store_dwordx4 v240, v[120:123], s[98:99] offset:16
	s_add_u32 s100, s36, 0x0
	s_addc_u32 s101, s37, 0
	global_load_dwordx4 v[172:175], v240, s[100:101] offset:512
	global_load_dwordx4 v[176:179], v240, s[100:101] offset:528
	s_ashr_i32 s98, s70, 5
	s_mul_i32 s98, s98, 0x9000
	s_add_u32 s98, s44, s98
	s_addc_u32 s99, s45, 0
	global_load_dwordx4 v[124:127], v241, s[98:99] offset:512
	global_load_dwordx4 v[120:123], v241, s[98:99] offset:528
	s_waitcnt vmcnt(18)
	v_pk_fma_f32 v[116:117], v[116:117], v[144:145], v[180:181]
	v_pk_fma_f32 v[118:119], v[118:119], v[146:147], v[182:183]
	v_pk_fma_f32 v[112:113], v[112:113], v[148:149], v[184:185]
	v_pk_fma_f32 v[114:115], v[114:115], v[150:151], v[186:187]
	s_add_u32 s98, s90, 0x10000
	s_addc_u32 s99, s91, 0
	global_store_dwordx4 v240, v[116:119], s[98:99]
	global_store_dwordx4 v240, v[112:115], s[98:99] offset:16
	s_add_u32 s100, s36, 0x10000
	s_addc_u32 s101, s37, 0
	global_load_dwordx4 v[180:183], v240, s[100:101] offset:512
	global_load_dwordx4 v[184:187], v240, s[100:101] offset:528
	s_waitcnt vmcnt(20)
	v_pk_fma_f32 v[108:109], v[108:109], v[144:145], v[188:189]
	v_pk_fma_f32 v[110:111], v[110:111], v[146:147], v[190:191]
	v_pk_fma_f32 v[104:105], v[104:105], v[148:149], v[192:193]
	v_pk_fma_f32 v[106:107], v[106:107], v[150:151], v[194:195]
	s_add_u32 s98, s90, 0x20000
	s_addc_u32 s99, s91, 0
	global_store_dwordx4 v240, v[108:111], s[98:99]
	global_store_dwordx4 v240, v[104:107], s[98:99] offset:16
	s_add_u32 s100, s36, 0x20000
	s_addc_u32 s101, s37, 0
	global_load_dwordx4 v[188:191], v240, s[100:101] offset:512
	global_load_dwordx4 v[192:195], v240, s[100:101] offset:528
	s_waitcnt vmcnt(22)
	v_pk_fma_f32 v[100:101], v[100:101], v[144:145], v[196:197]
	v_pk_fma_f32 v[102:103], v[102:103], v[146:147], v[198:199]
	v_pk_fma_f32 v[96:97], v[96:97], v[148:149], v[200:201]
	v_pk_fma_f32 v[98:99], v[98:99], v[150:151], v[202:203]
	s_add_u32 s98, s90, 0x30000
	s_addc_u32 s99, s91, 0
	global_store_dwordx4 v240, v[100:103], s[98:99]
	global_store_dwordx4 v240, v[96:99], s[98:99] offset:16
	s_add_u32 s100, s36, 0x30000
	s_addc_u32 s101, s37, 0
	global_load_dwordx4 v[196:199], v240, s[100:101] offset:512
	global_load_dwordx4 v[200:203], v240, s[100:101] offset:528
	s_waitcnt vmcnt(24)
	v_pk_fma_f32 v[92:93], v[92:93], v[144:145], v[208:209]
	v_pk_fma_f32 v[94:95], v[94:95], v[146:147], v[210:211]
	v_pk_fma_f32 v[88:89], v[88:89], v[148:149], v[212:213]
	v_pk_fma_f32 v[90:91], v[90:91], v[150:151], v[214:215]
	s_add_u32 s98, s90, 0x80000
	s_addc_u32 s99, s91, 0
	global_store_dwordx4 v240, v[92:95], s[98:99]
	global_store_dwordx4 v240, v[88:91], s[98:99] offset:16
	s_add_u32 s100, s36, 0x80000
	s_addc_u32 s101, s37, 0
	global_load_dwordx4 v[208:211], v240, s[100:101] offset:512
	global_load_dwordx4 v[212:215], v240, s[100:101] offset:528
	s_waitcnt vmcnt(26)
;     __device__ __forceinline__ void operator()(const f32x4 (&acc)[2][2][4][2], const pg8::Unit& u, int wr, int wc, int fr, int fq) const {
;         const int row0 = u.pm * 256 + wr * 64 + fr; const float* gp = gate + (size_t)(u.pm >> 5) * NMOD;
; #pragma unroll
;         for (int bj = 0; bj < 2; ++bj) {
;             const int col = u.pn * 256 + bj * 128 + wc * 32 + 8 * fq;
;             const f32x4 g0 = *(const f32x4*)(gp + col) * coef, g1 = *(const f32x4*)(gp + col + 4) * coef;
; #pragma unroll
;             for (int ai = 0; ai < 2; ++ai)
; #pragma unroll
;                 for (int m = 0; m < 4; ++m) {
;                     const size_t off = (size_t)(row0 + ai * 128 + m * 16) * DM + col;
;                     const f32x4 x0 = *(const f32x4*)(base + off), x1 = *(const f32x4*)(base + off + 4);
;                     *(f32x4*)(out + off) = x0 + g0 * acc[ai][bj][m][0]; *(f32x4*)(out + off + 4) = x1 + g1 * acc[ai][bj][m][1];
;                     if (m & 1) asm volatile("" ::: "memory");
;                 }
;         }
;     }
	v_pk_fma_f32 v[84:85], v[84:85], v[144:145], v[216:217]
	v_pk_fma_f32 v[86:87], v[86:87], v[146:147], v[218:219]
	v_pk_fma_f32 v[80:81], v[80:81], v[148:149], v[220:221]
	v_pk_fma_f32 v[82:83], v[82:83], v[150:151], v[222:223]
	s_add_u32 s98, s90, 0x90000
	s_addc_u32 s99, s91, 0
	global_store_dwordx4 v240, v[84:87], s[98:99]
	global_store_dwordx4 v240, v[80:83], s[98:99] offset:16
	s_add_u32 s100, s36, 0x90000
	s_addc_u32 s101, s37, 0
	global_load_dwordx4 v[216:219], v240, s[100:101] offset:512
	global_load_dwordx4 v[220:223], v240, s[100:101] offset:528
	s_waitcnt vmcnt(28)
	v_pk_fma_f32 v[76:77], v[76:77], v[144:145], v[224:225]
	v_pk_fma_f32 v[78:79], v[78:79], v[146:147], v[226:227]
	v_pk_fma_f32 v[72:73], v[72:73], v[148:149], v[228:229]
	v_pk_fma_f32 v[74:75], v[74:75], v[150:151], v[230:231]
	s_add_u32 s98, s90, 0xa0000
	s_addc_u32 s99, s91, 0
	global_store_dwordx4 v240, v[76:79], s[98:99]
	global_store_dwordx4 v240, v[72:75], s[98:99] offset:16
	s_add_u32 s100, s36, 0xa0000
	s_addc_u32 s101, s37, 0
	global_load_dwordx4 v[224:227], v240, s[100:101] offset:512
	global_load_dwordx4 v[228:231], v240, s[100:101] offset:528
	s_waitcnt vmcnt(30)
	v_pk_fma_f32 v[68:69], v[68:69], v[144:145], v[232:233]
	v_pk_fma_f32 v[70:71], v[70:71], v[146:147], v[234:235]
	v_pk_fma_f32 v[64:65], v[64:65], v[148:149], v[236:237]
	v_pk_fma_f32 v[66:67], v[66:67], v[150:151], v[238:239]
	s_add_u32 s98, s90, 0xb0000
	s_addc_u32 s99, s91, 0
	global_store_dwordx4 v240, v[68:71], s[98:99]
	global_store_dwordx4 v240, v[64:67], s[98:99] offset:16
	s_add_u32 s100, s36, 0xb0000
	s_addc_u32 s101, s37, 0
	global_load_dwordx4 v[232:235], v240, s[100:101] offset:512
	global_load_dwordx4 v[236:239], v240, s[100:101] offset:528
	s_waitcnt vmcnt(28)
	v_pk_mul_f32 v[120:121], v[120:121], 0.5 op_sel_hi:[1,0]
	v_pk_mul_f32 v[122:123], v[122:123], 0.5 op_sel_hi:[1,0]
	v_pk_mul_f32 v[124:125], v[124:125], 0.5 op_sel_hi:[1,0]
	v_pk_mul_f32 v[126:127], v[126:127], 0.5 op_sel_hi:[1,0]
	v_pk_fma_f32 v[60:61], v[60:61], v[124:125], v[172:173]
	v_pk_fma_f32 v[62:63], v[62:63], v[126:127], v[174:175]
	v_pk_fma_f32 v[56:57], v[56:57], v[120:121], v[176:177]
	v_pk_fma_f32 v[58:59], v[58:59], v[122:123], v[178:179]
	s_add_u32 s98, s90, 0x0
	s_addc_u32 s99, s91, 0
	global_store_dwordx4 v240, v[60:63], s[98:99] offset:512
	global_store_dwordx4 v240, v[56:59], s[98:99] offset:528
	s_waitcnt vmcnt(26)
	v_pk_fma_f32 v[52:53], v[52:53], v[124:125], v[180:181]
	v_pk_fma_f32 v[54:55], v[54:55], v[126:127], v[182:183]
	v_pk_fma_f32 v[48:49], v[48:49], v[120:121], v[184:185]
	v_pk_fma_f32 v[50:51], v[50:51], v[122:123], v[186:187]
	s_add_u32 s98, s90, 0x10000
	s_addc_u32 s99, s91, 0
	global_store_dwordx4 v240, v[52:55], s[98:99] offset:512
	global_store_dwordx4 v240, v[48:51], s[98:99] offset:528
	s_waitcnt vmcnt(24)
	v_pk_fma_f32 v[44:45], v[44:45], v[124:125], v[188:189]
	v_pk_fma_f32 v[46:47], v[46:47], v[126:127], v[190:191]
	v_pk_fma_f32 v[40:41], v[40:41], v[120:121], v[192:193]
	v_pk_fma_f32 v[42:43], v[42:43], v[122:123], v[194:195]
	s_add_u32 s98, s90, 0x20000
	s_addc_u32 s99, s91, 0
	global_store_dwordx4 v240, v[44:47], s[98:99] offset:512
	global_store_dwordx4 v240, v[40:43], s[98:99] offset:528
	s_waitcnt vmcnt(22)
	v_pk_fma_f32 v[36:37], v[36:37], v[124:125], v[196:197]
	v_pk_fma_f32 v[38:39], v[38:39], v[126:127], v[198:199]
	v_pk_fma_f32 v[32:33], v[32:33], v[120:121], v[200:201]
	v_pk_fma_f32 v[34:35], v[34:35], v[122:123], v[202:203]
	s_add_u32 s98, s90, 0x30000
	s_addc_u32 s99, s91, 0
	global_store_dwordx4 v240, v[36:39], s[98:99] offset:512
	global_store_dwordx4 v240, v[32:35], s[98:99] offset:528
	s_waitcnt vmcnt(20)
	v_pk_fma_f32 v[28:29], v[28:29], v[124:125], v[208:209]
	v_pk_fma_f32 v[30:31], v[30:31], v[126:127], v[210:211]
	v_pk_fma_f32 v[24:25], v[24:25], v[120:121], v[212:213]
	v_pk_fma_f32 v[26:27], v[26:27], v[122:123], v[214:215]
	s_add_u32 s98, s90, 0x80000
	s_addc_u32 s99, s91, 0
	global_store_dwordx4 v240, v[28:31], s[98:99] offset:512
	global_store_dwordx4 v240, v[24:27], s[98:99] offset:528
	s_waitcnt vmcnt(18)
	v_pk_fma_f32 v[20:21], v[20:21], v[124:125], v[216:217]
	v_pk_fma_f32 v[22:23], v[22:23], v[126:127], v[218:219]
	v_pk_fma_f32 v[16:17], v[16:17], v[120:121], v[220:221]
	v_pk_fma_f32 v[18:19], v[18:19], v[122:123], v[222:223]
	s_add_u32 s98, s90, 0x90000
	s_addc_u32 s99, s91, 0
	global_store_dwordx4 v240, v[20:23], s[98:99] offset:512
	global_store_dwordx4 v240, v[16:19], s[98:99] offset:528
	s_waitcnt vmcnt(16)
	v_pk_fma_f32 v[12:13], v[12:13], v[124:125], v[224:225]
	v_pk_fma_f32 v[14:15], v[14:15], v[126:127], v[226:227]
	v_pk_fma_f32 v[8:9], v[8:9], v[120:121], v[228:229]
	v_pk_fma_f32 v[10:11], v[10:11], v[122:123], v[230:231]
	s_add_u32 s98, s90, 0xa0000
	s_addc_u32 s99, s91, 0
	global_store_dwordx4 v240, v[12:15], s[98:99] offset:512
	global_store_dwordx4 v240, v[8:11], s[98:99] offset:528
	s_waitcnt vmcnt(14)
	v_pk_fma_f32 v[4:5], v[4:5], v[124:125], v[232:233]
	v_pk_fma_f32 v[6:7], v[6:7], v[126:127], v[234:235]
	v_pk_fma_f32 v[0:1], v[0:1], v[120:121], v[236:237]
	v_pk_fma_f32 v[2:3], v[2:3], v[122:123], v[238:239]
	s_add_u32 s98, s90, 0xb0000
	s_addc_u32 s99, s91, 0
	global_store_dwordx4 v240, v[4:7], s[98:99] offset:512
	global_store_dwordx4 v240, v[0:3], s[98:99] offset:528
	s_and_b64 vcc, exec, s[6:7]
	s_mov_b64 s[24:25], -1
	s_cbranch_vccnz .LBB0_220
	s_andn2_b64 vcc, exec, s[10:11]
	s_cbranch_vccnz .LBB0_219
	s_barrier
	s_branch .LBB0_219

;     __device__ __forceinline__ void operator()(const f32x4 (&acc)[2][2][4][2], const pg8::Unit& u, int wr, int wc, int fr, int fq) const {
;         const int row0 = u.pm * 256 + wr * 64 + fr; const float* gp = gate + (size_t)(u.pm >> 5) * NMOD;
; #pragma unroll
;         for (int bj = 0; bj < 2; ++bj) {
;             const int col = u.pn * 256 + bj * 128 + wc * 32 + 8 * fq;
;             const f32x4 g0 = *(const f32x4*)(gp + col) * coef, g1 = *(const f32x4*)(gp + col + 4) * coef;
; #pragma unroll
;             for (int ai = 0; ai < 2; ++ai)
; #pragma unroll
;                 for (int m = 0; m < 4; ++m) {
;                     const size_t off = (size_t)(row0 + ai * 128 + m * 16) * DM + col;
;                     const f32x4 x0 = *(const f32x4*)(base + off), x1 = *(const f32x4*)(base + off + 4);
;                     *(f32x4*)(out + off) = x0 + g0 * acc[ai][bj][m][0]; *(f32x4*)(out + off + 4) = x1 + g1 * acc[ai][bj][m][1];
;                     if (m & 1) asm volatile("" ::: "memory");
;                 }
;         }
;     }
.LBB0_1173:
	v_lshl_add_u32 v240, s28, 8, v164
	v_lshl_add_u32 v241, s53, 8, v167
	v_lshlrev_b32_e32 v240, 10, v240
	v_add_lshl_u32 v240, v240, v241, 2
	v_lshlrev_b32_e32 v241, 2, v241
	s_ashr_i32 s98, s28, 5
	s_mul_i32 s98, s98, 0x9000
	s_add_u32 s98, s45, s98
	s_addc_u32 s99, s46, 0
	global_load_dwordx4 v[152:155], v241, s[98:99]
	global_load_dwordx4 v[156:159], v241, s[98:99] offset:16
	s_add_u32 s100, s90, 0x0
	s_addc_u32 s101, s91, 0
	global_load_dwordx4 v[172:175], v240, s[100:101]
	global_load_dwordx4 v[176:179], v240, s[100:101] offset:16
	s_add_u32 s100, s90, 0x10000
	s_addc_u32 s101, s91, 0
	global_load_dwordx4 v[180:183], v240, s[100:101]
	global_load_dwordx4 v[184:187], v240, s[100:101] offset:16
	s_add_u32 s100, s90, 0x20000
	s_addc_u32 s101, s91, 0
	global_load_dwordx4 v[188:191], v240, s[100:101]
	global_load_dwordx4 v[192:195], v240, s[100:101] offset:16
	s_add_u32 s100, s90, 0x30000
	s_addc_u32 s101, s91, 0
	global_load_dwordx4 v[196:199], v240, s[100:101]
	global_load_dwordx4 v[200:203], v240, s[100:101] offset:16
	s_add_u32 s100, s90, 0x80000
	s_addc_u32 s101, s91, 0
	global_load_dwordx4 v[208:211], v240, s[100:101]
	global_load_dwordx4 v[212:215], v240, s[100:101] offset:16
	s_add_u32 s100, s90, 0x90000
	s_addc_u32 s101, s91, 0
	global_load_dwordx4 v[216:219], v240, s[100:101]
	global_load_dwordx4 v[220:223], v240, s[100:101] offset:16
	s_add_u32 s100, s90, 0xa0000
	s_addc_u32 s101, s91, 0
	global_load_dwordx4 v[224:227], v240, s[100:101]
	global_load_dwordx4 v[228:231], v240, s[100:101] offset:16
	s_add_u32 s100, s90, 0xb0000
	s_addc_u32 s101, s91, 0
	global_load_dwordx4 v[232:235], v240, s[100:101]
	global_load_dwordx4 v[236:239], v240, s[100:101] offset:16
	s_waitcnt vmcnt(16)
	s_waitcnt vmcnt(14)
	v_pk_fma_f32 v[124:125], v[124:125], v[152:153], v[172:173]
	v_pk_fma_f32 v[126:127], v[126:127], v[154:155], v[174:175]
	v_pk_fma_f32 v[120:121], v[120:121], v[156:157], v[176:177]
	v_pk_fma_f32 v[122:123], v[122:123], v[158:159], v[178:179]
	s_add_u32 s98, s90, 0x0
	s_addc_u32 s99, s91, 0
	global_store_dwordx4 v240, v[124:127], s[98:99]
	global_store_dwordx4 v240, v[120:123], s[98:99] offset:16
	s_add_u32 s100, s90, 0x0
	s_addc_u32 s101, s91, 0
	global_load_dwordx4 v[172:175], v240, s[100:101] offset:512
	global_load_dwordx4 v[176:179], v240, s[100:101] offset:528
	s_ashr_i32 s98, s28, 5
	s_mul_i32 s98, s98, 0x9000
	s_add_u32 s98, s45, s98
	s_addc_u32 s99, s46, 0
	global_load_dwordx4 v[124:127], v241, s[98:99] offset:512
	global_load_dwordx4 v[120:123], v241, s[98:99] offset:528
	s_waitcnt vmcnt(18)
	v_pk_fma_f32 v[116:117], v[116:117], v[152:153], v[180:181]
	v_pk_fma_f32 v[118:119], v[118:119], v[154:155], v[182:183]
	v_pk_fma_f32 v[112:113], v[112:113], v[156:157], v[184:185]
	v_pk_fma_f32 v[114:115], v[114:115], v[158:159], v[186:187]
	s_add_u32 s98, s90, 0x10000
	s_addc_u32 s99, s91, 0
	global_store_dwordx4 v240, v[116:119], s[98:99]
	global_store_dwordx4 v240, v[112:115], s[98:99] offset:16
	s_add_u32 s100, s90, 0x10000
	s_addc_u32 s101, s91, 0
	global_load_dwordx4 v[180:183], v240, s[100:101] offset:512
	global_load_dwordx4 v[184:187], v240, s[100:101] offset:528
	s_waitcnt vmcnt(20)
	v_pk_fma_f32 v[108:109], v[108:109], v[152:153], v[188:189]
	v_pk_fma_f32 v[110:111], v[110:111], v[154:155], v[190:191]
	v_pk_fma_f32 v[104:105], v[104:105], v[156:157], v[192:193]
	v_pk_fma_f32 v[106:107], v[106:107], v[158:159], v[194:195]
	s_add_u32 s98, s90, 0x20000
	s_addc_u32 s99, s91, 0
	global_store_dwordx4 v240, v[108:111], s[98:99]
	global_store_dwordx4 v240, v[104:107], s[98:99] offset:16
	s_add_u32 s100, s90, 0x20000
	s_addc_u32 s101, s91, 0
	global_load_dwordx4 v[188:191], v240, s[100:101] offset:512
	global_load_dwordx4 v[192:195], v240, s[100:101] offset:528
	s_waitcnt vmcnt(22)
	v_pk_fma_f32 v[100:101], v[100:101], v[152:153], v[196:197]
	v_pk_fma_f32 v[102:103], v[102:103], v[154:155], v[198:199]
	v_pk_fma_f32 v[96:97], v[96:97], v[156:157], v[200:201]
	v_pk_fma_f32 v[98:99], v[98:99], v[158:159], v[202:203]
	s_add_u32 s98, s90, 0x30000
	s_addc_u32 s99, s91, 0
	global_store_dwordx4 v240, v[100:103], s[98:99]
	global_store_dwordx4 v240, v[96:99], s[98:99] offset:16
	s_add_u32 s100, s90, 0x30000
	s_addc_u32 s101, s91, 0
	global_load_dwordx4 v[196:199], v240, s[100:101] offset:512
	global_load_dwordx4 v[200:203], v240, s[100:101] offset:528
	s_waitcnt vmcnt(24)
	v_pk_fma_f32 v[92:93], v[92:93], v[152:153], v[208:209]
	v_pk_fma_f32 v[94:95], v[94:95], v[154:155], v[210:211]
	v_pk_fma_f32 v[88:89], v[88:89], v[156:157], v[212:213]
	v_pk_fma_f32 v[90:91], v[90:91], v[158:159], v[214:215]
	s_add_u32 s98, s90, 0x80000
	s_addc_u32 s99, s91, 0
	global_store_dwordx4 v240, v[92:95], s[98:99]
	global_store_dwordx4 v240, v[88:91], s[98:99] offset:16
	s_add_u32 s100, s90, 0x80000
	s_addc_u32 s101, s91, 0
	global_load_dwordx4 v[208:211], v240, s[100:101] offset:512
	global_load_dwordx4 v[212:215], v240, s[100:101] offset:528
	s_waitcnt vmcnt(26)
;     __device__ __forceinline__ void operator()(const f32x4 (&acc)[2][2][4][2], const pg8::Unit& u, int wr, int wc, int fr, int fq) const {
;         const int row0 = u.pm * 256 + wr * 64 + fr; const float* gp = gate + (size_t)(u.pm >> 5) * NMOD;
; #pragma unroll
;         for (int bj = 0; bj < 2; ++bj) {
;             const int col = u.pn * 256 + bj * 128 + wc * 32 + 8 * fq;
;             const f32x4 g0 = *(const f32x4*)(gp + col) * coef, g1 = *(const f32x4*)(gp + col + 4) * coef;
; #pragma unroll
;             for (int ai = 0; ai < 2; ++ai)
; #pragma unroll
;                 for (int m = 0; m < 4; ++m) {
;                     const size_t off = (size_t)(row0 + ai * 128 + m * 16) * DM + col;
;                     const f32x4 x0 = *(const f32x4*)(base + off), x1 = *(const f32x4*)(base + off + 4);
;                     *(f32x4*)(out + off) = x0 + g0 * acc[ai][bj][m][0]; *(f32x4*)(out + off + 4) = x1 + g1 * acc[ai][bj][m][1];
;                     if (m & 1) asm volatile("" ::: "memory");
;                 }
;         }
;     }
	v_pk_fma_f32 v[84:85], v[84:85], v[152:153], v[216:217]
	v_pk_fma_f32 v[86:87], v[86:87], v[154:155], v[218:219]
	v_pk_fma_f32 v[80:81], v[80:81], v[156:157], v[220:221]
	v_pk_fma_f32 v[82:83], v[82:83], v[158:159], v[222:223]
	s_add_u32 s98, s90, 0x90000
	s_addc_u32 s99, s91, 0
	global_store_dwordx4 v240, v[84:87], s[98:99]
	global_store_dwordx4 v240, v[80:83], s[98:99] offset:16
	s_add_u32 s100, s90, 0x90000
	s_addc_u32 s101, s91, 0
	global_load_dwordx4 v[216:219], v240, s[100:101] offset:512
	global_load_dwordx4 v[220:223], v240, s[100:101] offset:528
	s_waitcnt vmcnt(28)
	v_pk_fma_f32 v[76:77], v[76:77], v[152:153], v[224:225]
	v_pk_fma_f32 v[78:79], v[78:79], v[154:155], v[226:227]
	v_pk_fma_f32 v[72:73], v[72:73], v[156:157], v[228:229]
	v_pk_fma_f32 v[74:75], v[74:75], v[158:159], v[230:231]
	s_add_u32 s98, s90, 0xa0000
	s_addc_u32 s99, s91, 0
	global_store_dwordx4 v240, v[76:79], s[98:99]
	global_store_dwordx4 v240, v[72:75], s[98:99] offset:16
	s_add_u32 s100, s90, 0xa0000
	s_addc_u32 s101, s91, 0
	global_load_dwordx4 v[224:227], v240, s[100:101] offset:512
	global_load_dwordx4 v[228:231], v240, s[100:101] offset:528
	s_waitcnt vmcnt(30)
	v_pk_fma_f32 v[68:69], v[68:69], v[152:153], v[232:233]
	v_pk_fma_f32 v[70:71], v[70:71], v[154:155], v[234:235]
	v_pk_fma_f32 v[64:65], v[64:65], v[156:157], v[236:237]
	v_pk_fma_f32 v[66:67], v[66:67], v[158:159], v[238:239]
	s_add_u32 s98, s90, 0xb0000
	s_addc_u32 s99, s91, 0
	global_store_dwordx4 v240, v[68:71], s[98:99]
	global_store_dwordx4 v240, v[64:67], s[98:99] offset:16
	s_add_u32 s100, s90, 0xb0000
	s_addc_u32 s101, s91, 0
	global_load_dwordx4 v[232:235], v240, s[100:101] offset:512
	global_load_dwordx4 v[236:239], v240, s[100:101] offset:528
	s_waitcnt vmcnt(28)
	v_pk_fma_f32 v[60:61], v[60:61], v[124:125], v[172:173]
	v_pk_fma_f32 v[62:63], v[62:63], v[126:127], v[174:175]
	v_pk_fma_f32 v[56:57], v[56:57], v[120:121], v[176:177]
	v_pk_fma_f32 v[58:59], v[58:59], v[122:123], v[178:179]
	s_add_u32 s98, s90, 0x0
	s_addc_u32 s99, s91, 0
	global_store_dwordx4 v240, v[60:63], s[98:99] offset:512
	global_store_dwordx4 v240, v[56:59], s[98:99] offset:528
	s_waitcnt vmcnt(26)
	v_pk_fma_f32 v[52:53], v[52:53], v[124:125], v[180:181]
	v_pk_fma_f32 v[54:55], v[54:55], v[126:127], v[182:183]
	v_pk_fma_f32 v[48:49], v[48:49], v[120:121], v[184:185]
	v_pk_fma_f32 v[50:51], v[50:51], v[122:123], v[186:187]
	s_add_u32 s98, s90, 0x10000
	s_addc_u32 s99, s91, 0
	global_store_dwordx4 v240, v[52:55], s[98:99] offset:512
	global_store_dwordx4 v240, v[48:51], s[98:99] offset:528
	s_waitcnt vmcnt(24)
	v_pk_fma_f32 v[44:45], v[44:45], v[124:125], v[188:189]
	v_pk_fma_f32 v[46:47], v[46:47], v[126:127], v[190:191]
	v_pk_fma_f32 v[40:41], v[40:41], v[120:121], v[192:193]
	v_pk_fma_f32 v[42:43], v[42:43], v[122:123], v[194:195]
	s_add_u32 s98, s90, 0x20000
	s_addc_u32 s99, s91, 0
	global_store_dwordx4 v240, v[44:47], s[98:99] offset:512
	global_store_dwordx4 v240, v[40:43], s[98:99] offset:528
	s_waitcnt vmcnt(22)
	v_pk_fma_f32 v[36:37], v[36:37], v[124:125], v[196:197]
	v_pk_fma_f32 v[38:39], v[38:39], v[126:127], v[198:199]
	v_pk_fma_f32 v[32:33], v[32:33], v[120:121], v[200:201]
	v_pk_fma_f32 v[34:35], v[34:35], v[122:123], v[202:203]
	s_add_u32 s98, s90, 0x30000
	s_addc_u32 s99, s91, 0
	global_store_dwordx4 v240, v[36:39], s[98:99] offset:512
	global_store_dwordx4 v240, v[32:35], s[98:99] offset:528
	s_waitcnt vmcnt(20)
	v_pk_fma_f32 v[28:29], v[28:29], v[124:125], v[208:209]
	v_pk_fma_f32 v[30:31], v[30:31], v[126:127], v[210:211]
	v_pk_fma_f32 v[24:25], v[24:25], v[120:121], v[212:213]
	v_pk_fma_f32 v[26:27], v[26:27], v[122:123], v[214:215]
	s_add_u32 s98, s90, 0x80000
	s_addc_u32 s99, s91, 0
	global_store_dwordx4 v240, v[28:31], s[98:99] offset:512
	global_store_dwordx4 v240, v[24:27], s[98:99] offset:528
	s_waitcnt vmcnt(18)
	v_pk_fma_f32 v[20:21], v[20:21], v[124:125], v[216:217]
	v_pk_fma_f32 v[22:23], v[22:23], v[126:127], v[218:219]
	v_pk_fma_f32 v[16:17], v[16:17], v[120:121], v[220:221]
	v_pk_fma_f32 v[18:19], v[18:19], v[122:123], v[222:223]
	s_add_u32 s98, s90, 0x90000
	s_addc_u32 s99, s91, 0
	global_store_dwordx4 v240, v[20:23], s[98:99] offset:512
	global_store_dwordx4 v240, v[16:19], s[98:99] offset:528
	s_waitcnt vmcnt(16)
	v_pk_fma_f32 v[12:13], v[12:13], v[124:125], v[224:225]
	v_pk_fma_f32 v[14:15], v[14:15], v[126:127], v[226:227]
	v_pk_fma_f32 v[8:9], v[8:9], v[120:121], v[228:229]
	v_pk_fma_f32 v[10:11], v[10:11], v[122:123], v[230:231]
	s_add_u32 s98, s90, 0xa0000
	s_addc_u32 s99, s91, 0
	global_store_dwordx4 v240, v[12:15], s[98:99] offset:512
	global_store_dwordx4 v240, v[8:11], s[98:99] offset:528
	s_waitcnt vmcnt(14)
	v_pk_fma_f32 v[4:5], v[4:5], v[124:125], v[232:233]
	v_pk_fma_f32 v[6:7], v[6:7], v[126:127], v[234:235]
	v_pk_fma_f32 v[0:1], v[0:1], v[120:121], v[236:237]
	v_pk_fma_f32 v[2:3], v[2:3], v[122:123], v[238:239]
	s_add_u32 s98, s90, 0xb0000
	s_addc_u32 s99, s91, 0
	global_store_dwordx4 v240, v[4:7], s[98:99] offset:512
	global_store_dwordx4 v240, v[0:3], s[98:99] offset:528
	s_andn2_b64 vcc, exec, s[6:7]
	s_mov_b64 s[6:7], -1
	s_cbranch_vccnz .LBB0_1162
	s_andn2_b64 vcc, exec, s[0:1]
	s_cbranch_vccnz .LBB0_1161
	s_barrier
	s_branch .LBB0_1161

;     __device__ __forceinline__ void operator()(const f32x4 (&acc)[2][2][4][2], const pg8::Unit& u, int wr, int wc, int fr, int fq) const {
;         const int row0 = u.pm * 256 + wr * 64 + fr; const float* gp = gate + (size_t)(u.pm >> 5) * NMOD;
; #pragma unroll
;         for (int bj = 0; bj < 2; ++bj) {
;             const int col = u.pn * 256 + bj * 128 + wc * 32 + 8 * fq;
;             const f32x4 g0 = *(const f32x4*)(gp + col) * coef, g1 = *(const f32x4*)(gp + col + 4) * coef;
; #pragma unroll
;             for (int ai = 0; ai < 2; ++ai)
; #pragma unroll
;                 for (int m = 0; m < 4; ++m) {
;                     const size_t off = (size_t)(row0 + ai * 128 + m * 16) * DM + col;
;                     const f32x4 x0 = *(const f32x4*)(base + off), x1 = *(const f32x4*)(base + off + 4);
;                     *(f32x4*)(out + off) = x0 + g0 * acc[ai][bj][m][0]; *(f32x4*)(out + off + 4) = x1 + g1 * acc[ai][bj][m][1];
;                     if (m & 1) asm volatile("" ::: "memory");
;                 }
;         }
;     }
.LBB0_1396:
	v_lshl_add_u32 v240, s47, 8, v156
	v_lshl_add_u32 v241, s48, 8, v158
	v_lshlrev_b32_e32 v240, 10, v240
	v_add_lshl_u32 v240, v240, v241, 2
	v_lshlrev_b32_e32 v241, 2, v241
	s_ashr_i32 s98, s47, 5
	s_mul_i32 s98, s98, 0x9000
	s_add_u32 s98, s38, s98
	s_addc_u32 s99, s39, 0
	global_load_dwordx4 v[144:147], v241, s[98:99]
	global_load_dwordx4 v[148:151], v241, s[98:99] offset:16
	s_add_u32 s100, s90, 0x0
	s_addc_u32 s101, s91, 0
	global_load_dwordx4 v[172:175], v240, s[100:101]
	global_load_dwordx4 v[176:179], v240, s[100:101] offset:16
	s_add_u32 s100, s90, 0x10000
	s_addc_u32 s101, s91, 0
	global_load_dwordx4 v[180:183], v240, s[100:101]
	global_load_dwordx4 v[184:187], v240, s[100:101] offset:16
	s_add_u32 s100, s90, 0x20000
	s_addc_u32 s101, s91, 0
	global_load_dwordx4 v[188:191], v240, s[100:101]
	global_load_dwordx4 v[192:195], v240, s[100:101] offset:16
	s_add_u32 s100, s90, 0x30000
	s_addc_u32 s101, s91, 0
	global_load_dwordx4 v[196:199], v240, s[100:101]
	global_load_dwordx4 v[200:203], v240, s[100:101] offset:16
	s_add_u32 s100, s90, 0x80000
	s_addc_u32 s101, s91, 0
	global_load_dwordx4 v[208:211], v240, s[100:101]
	global_load_dwordx4 v[212:215], v240, s[100:101] offset:16
	s_add_u32 s100, s90, 0x90000
	s_addc_u32 s101, s91, 0
	global_load_dwordx4 v[216:219], v240, s[100:101]
	global_load_dwordx4 v[220:223], v240, s[100:101] offset:16
	s_add_u32 s100, s90, 0xa0000
	s_addc_u32 s101, s91, 0
	global_load_dwordx4 v[224:227], v240, s[100:101]
	global_load_dwordx4 v[228:231], v240, s[100:101] offset:16
	s_add_u32 s100, s90, 0xb0000
	s_addc_u32 s101, s91, 0
	global_load_dwordx4 v[232:235], v240, s[100:101]
	global_load_dwordx4 v[236:239], v240, s[100:101] offset:16
	s_waitcnt vmcnt(16)
	v_pk_mul_f32 v[144:145], v[144:145], 0.5 op_sel_hi:[1,0]
	v_pk_mul_f32 v[146:147], v[146:147], 0.5 op_sel_hi:[1,0]
	v_pk_mul_f32 v[148:149], v[148:149], 0.5 op_sel_hi:[1,0]
	v_pk_mul_f32 v[150:151], v[150:151], 0.5 op_sel_hi:[1,0]
	s_waitcnt vmcnt(14)
	v_pk_fma_f32 v[124:125], v[124:125], v[144:145], v[172:173]
	v_pk_fma_f32 v[126:127], v[126:127], v[146:147], v[174:175]
	v_pk_fma_f32 v[120:121], v[120:121], v[148:149], v[176:177]
	v_pk_fma_f32 v[122:123], v[122:123], v[150:151], v[178:179]
	s_add_u32 s98, s90, 0x0
	s_addc_u32 s99, s91, 0
	global_store_dwordx4 v240, v[124:127], s[98:99]
	global_store_dwordx4 v240, v[120:123], s[98:99] offset:16
	s_add_u32 s100, s90, 0x0
	s_addc_u32 s101, s91, 0
	global_load_dwordx4 v[172:175], v240, s[100:101] offset:512
	global_load_dwordx4 v[176:179], v240, s[100:101] offset:528
	s_ashr_i32 s98, s47, 5
	s_mul_i32 s98, s98, 0x9000
	s_add_u32 s98, s38, s98
	s_addc_u32 s99, s39, 0
	global_load_dwordx4 v[124:127], v241, s[98:99] offset:512
	global_load_dwordx4 v[120:123], v241, s[98:99] offset:528
	s_waitcnt vmcnt(18)
	v_pk_fma_f32 v[116:117], v[116:117], v[144:145], v[180:181]
	v_pk_fma_f32 v[118:119], v[118:119], v[146:147], v[182:183]
	v_pk_fma_f32 v[112:113], v[112:113], v[148:149], v[184:185]
	v_pk_fma_f32 v[114:115], v[114:115], v[150:151], v[186:187]
	s_add_u32 s98, s90, 0x10000
	s_addc_u32 s99, s91, 0
	global_store_dwordx4 v240, v[116:119], s[98:99]
	global_store_dwordx4 v240, v[112:115], s[98:99] offset:16
	s_add_u32 s100, s90, 0x10000
	s_addc_u32 s101, s91, 0
	global_load_dwordx4 v[180:183], v240, s[100:101] offset:512
	global_load_dwordx4 v[184:187], v240, s[100:101] offset:528
	s_waitcnt vmcnt(20)
	v_pk_fma_f32 v[108:109], v[108:109], v[144:145], v[188:189]
	v_pk_fma_f32 v[110:111], v[110:111], v[146:147], v[190:191]
	v_pk_fma_f32 v[104:105], v[104:105], v[148:149], v[192:193]
	v_pk_fma_f32 v[106:107], v[106:107], v[150:151], v[194:195]
	s_add_u32 s98, s90, 0x20000
	s_addc_u32 s99, s91, 0
	global_store_dwordx4 v240, v[108:111], s[98:99]
	global_store_dwordx4 v240, v[104:107], s[98:99] offset:16
	s_add_u32 s100, s90, 0x20000
	s_addc_u32 s101, s91, 0
	global_load_dwordx4 v[188:191], v240, s[100:101] offset:512
	global_load_dwordx4 v[192:195], v240, s[100:101] offset:528
	s_waitcnt vmcnt(22)
	v_pk_fma_f32 v[100:101], v[100:101], v[144:145], v[196:197]
	v_pk_fma_f32 v[102:103], v[102:103], v[146:147], v[198:199]
	v_pk_fma_f32 v[96:97], v[96:97], v[148:149], v[200:201]
	v_pk_fma_f32 v[98:99], v[98:99], v[150:151], v[202:203]
	s_add_u32 s98, s90, 0x30000
	s_addc_u32 s99, s91, 0
	global_store_dwordx4 v240, v[100:103], s[98:99]
	global_store_dwordx4 v240, v[96:99], s[98:99] offset:16
	s_add_u32 s100, s90, 0x30000
	s_addc_u32 s101, s91, 0
	global_load_dwordx4 v[196:199], v240, s[100:101] offset:512
	global_load_dwordx4 v[200:203], v240, s[100:101] offset:528
	s_waitcnt vmcnt(24)
	v_pk_fma_f32 v[92:93], v[92:93], v[144:145], v[208:209]
	v_pk_fma_f32 v[94:95], v[94:95], v[146:147], v[210:211]
	v_pk_fma_f32 v[88:89], v[88:89], v[148:149], v[212:213]
	v_pk_fma_f32 v[90:91], v[90:91], v[150:151], v[214:215]
	s_add_u32 s98, s90, 0x80000
	s_addc_u32 s99, s91, 0
	global_store_dwordx4 v240, v[92:95], s[98:99]
	global_store_dwordx4 v240, v[88:91], s[98:99] offset:16
	s_add_u32 s100, s90, 0x80000
	s_addc_u32 s101, s91, 0
	global_load_dwordx4 v[208:211], v240, s[100:101] offset:512
	global_load_dwordx4 v[212:215], v240, s[100:101] offset:528
	s_waitcnt vmcnt(26)
;     __device__ __forceinline__ void operator()(const f32x4 (&acc)[2][2][4][2], const pg8::Unit& u, int wr, int wc, int fr, int fq) const {
;         const int row0 = u.pm * 256 + wr * 64 + fr; const float* gp = gate + (size_t)(u.pm >> 5) * NMOD;
; #pragma unroll
;         for (int bj = 0; bj < 2; ++bj) {
;             const int col = u.pn * 256 + bj * 128 + wc * 32 + 8 * fq;
;             const f32x4 g0 = *(const f32x4*)(gp + col) * coef, g1 = *(const f32x4*)(gp + col + 4) * coef;
; #pragma unroll
;             for (int ai = 0; ai < 2; ++ai)
; #pragma unroll
;                 for (int m = 0; m < 4; ++m) {
;                     const size_t off = (size_t)(row0 + ai * 128 + m * 16) * DM + col;
;                     const f32x4 x0 = *(const f32x4*)(base + off), x1 = *(const f32x4*)(base + off + 4);
;                     *(f32x4*)(out + off) = x0 + g0 * acc[ai][bj][m][0]; *(f32x4*)(out + off + 4) = x1 + g1 * acc[ai][bj][m][1];
;                     if (m & 1) asm volatile("" ::: "memory");
;                 }
;         }
;     }
	v_pk_fma_f32 v[84:85], v[84:85], v[144:145], v[216:217]
	v_pk_fma_f32 v[86:87], v[86:87], v[146:147], v[218:219]
	v_pk_fma_f32 v[80:81], v[80:81], v[148:149], v[220:221]
	v_pk_fma_f32 v[82:83], v[82:83], v[150:151], v[222:223]
	s_add_u32 s98, s90, 0x90000
	s_addc_u32 s99, s91, 0
	global_store_dwordx4 v240, v[84:87], s[98:99]
	global_store_dwordx4 v240, v[80:83], s[98:99] offset:16
	s_add_u32 s100, s90, 0x90000
	s_addc_u32 s101, s91, 0
	global_load_dwordx4 v[216:219], v240, s[100:101] offset:512
	global_load_dwordx4 v[220:223], v240, s[100:101] offset:528
	s_waitcnt vmcnt(28)
	v_pk_fma_f32 v[76:77], v[76:77], v[144:145], v[224:225]
	v_pk_fma_f32 v[78:79], v[78:79], v[146:147], v[226:227]
	v_pk_fma_f32 v[72:73], v[72:73], v[148:149], v[228:229]
	v_pk_fma_f32 v[74:75], v[74:75], v[150:151], v[230:231]
	s_add_u32 s98, s90, 0xa0000
	s_addc_u32 s99, s91, 0
	global_store_dwordx4 v240, v[76:79], s[98:99]
	global_store_dwordx4 v240, v[72:75], s[98:99] offset:16
	s_add_u32 s100, s90, 0xa0000
	s_addc_u32 s101, s91, 0
	global_load_dwordx4 v[224:227], v240, s[100:101] offset:512
	global_load_dwordx4 v[228:231], v240, s[100:101] offset:528
	s_waitcnt vmcnt(30)
	v_pk_fma_f32 v[68:69], v[68:69], v[144:145], v[232:233]
	v_pk_fma_f32 v[70:71], v[70:71], v[146:147], v[234:235]
	v_pk_fma_f32 v[64:65], v[64:65], v[148:149], v[236:237]
	v_pk_fma_f32 v[66:67], v[66:67], v[150:151], v[238:239]
	s_add_u32 s98, s90, 0xb0000
	s_addc_u32 s99, s91, 0
	global_store_dwordx4 v240, v[68:71], s[98:99]
	global_store_dwordx4 v240, v[64:67], s[98:99] offset:16
	s_add_u32 s100, s90, 0xb0000
	s_addc_u32 s101, s91, 0
	global_load_dwordx4 v[232:235], v240, s[100:101] offset:512
	global_load_dwordx4 v[236:239], v240, s[100:101] offset:528
	s_waitcnt vmcnt(28)
	v_pk_mul_f32 v[120:121], v[120:121], 0.5 op_sel_hi:[1,0]
	v_pk_mul_f32 v[122:123], v[122:123], 0.5 op_sel_hi:[1,0]
	v_pk_mul_f32 v[124:125], v[124:125], 0.5 op_sel_hi:[1,0]
	v_pk_mul_f32 v[126:127], v[126:127], 0.5 op_sel_hi:[1,0]
	v_pk_fma_f32 v[60:61], v[60:61], v[124:125], v[172:173]
	v_pk_fma_f32 v[62:63], v[62:63], v[126:127], v[174:175]
	v_pk_fma_f32 v[56:57], v[56:57], v[120:121], v[176:177]
	v_pk_fma_f32 v[58:59], v[58:59], v[122:123], v[178:179]
	s_add_u32 s98, s90, 0x0
	s_addc_u32 s99, s91, 0
	global_store_dwordx4 v240, v[60:63], s[98:99] offset:512
	global_store_dwordx4 v240, v[56:59], s[98:99] offset:528
	s_waitcnt vmcnt(26)
	v_pk_fma_f32 v[52:53], v[52:53], v[124:125], v[180:181]
	v_pk_fma_f32 v[54:55], v[54:55], v[126:127], v[182:183]
	v_pk_fma_f32 v[48:49], v[48:49], v[120:121], v[184:185]
	v_pk_fma_f32 v[50:51], v[50:51], v[122:123], v[186:187]
	s_add_u32 s98, s90, 0x10000
	s_addc_u32 s99, s91, 0
	global_store_dwordx4 v240, v[52:55], s[98:99] offset:512
	global_store_dwordx4 v240, v[48:51], s[98:99] offset:528
	s_waitcnt vmcnt(24)
	v_pk_fma_f32 v[44:45], v[44:45], v[124:125], v[188:189]
	v_pk_fma_f32 v[46:47], v[46:47], v[126:127], v[190:191]
	v_pk_fma_f32 v[40:41], v[40:41], v[120:121], v[192:193]
	v_pk_fma_f32 v[42:43], v[42:43], v[122:123], v[194:195]
	s_add_u32 s98, s90, 0x20000
	s_addc_u32 s99, s91, 0
	global_store_dwordx4 v240, v[44:47], s[98:99] offset:512
	global_store_dwordx4 v240, v[40:43], s[98:99] offset:528
	s_waitcnt vmcnt(22)
	v_pk_fma_f32 v[36:37], v[36:37], v[124:125], v[196:197]
	v_pk_fma_f32 v[38:39], v[38:39], v[126:127], v[198:199]
	v_pk_fma_f32 v[32:33], v[32:33], v[120:121], v[200:201]
	v_pk_fma_f32 v[34:35], v[34:35], v[122:123], v[202:203]
	s_add_u32 s98, s90, 0x30000
	s_addc_u32 s99, s91, 0
	global_store_dwordx4 v240, v[36:39], s[98:99] offset:512
	global_store_dwordx4 v240, v[32:35], s[98:99] offset:528
	s_waitcnt vmcnt(20)
	v_pk_fma_f32 v[28:29], v[28:29], v[124:125], v[208:209]
	v_pk_fma_f32 v[30:31], v[30:31], v[126:127], v[210:211]
	v_pk_fma_f32 v[24:25], v[24:25], v[120:121], v[212:213]
	v_pk_fma_f32 v[26:27], v[26:27], v[122:123], v[214:215]
	s_add_u32 s98, s90, 0x80000
	s_addc_u32 s99, s91, 0
	global_store_dwordx4 v240, v[28:31], s[98:99] offset:512
	global_store_dwordx4 v240, v[24:27], s[98:99] offset:528
	s_waitcnt vmcnt(18)
	v_pk_fma_f32 v[20:21], v[20:21], v[124:125], v[216:217]
	v_pk_fma_f32 v[22:23], v[22:23], v[126:127], v[218:219]
	v_pk_fma_f32 v[16:17], v[16:17], v[120:121], v[220:221]
	v_pk_fma_f32 v[18:19], v[18:19], v[122:123], v[222:223]
	s_add_u32 s98, s90, 0x90000
	s_addc_u32 s99, s91, 0
	global_store_dwordx4 v240, v[20:23], s[98:99] offset:512
	global_store_dwordx4 v240, v[16:19], s[98:99] offset:528
	s_waitcnt vmcnt(16)
	v_pk_fma_f32 v[12:13], v[12:13], v[124:125], v[224:225]
	v_pk_fma_f32 v[14:15], v[14:15], v[126:127], v[226:227]
	v_pk_fma_f32 v[8:9], v[8:9], v[120:121], v[228:229]
	v_pk_fma_f32 v[10:11], v[10:11], v[122:123], v[230:231]
	s_add_u32 s98, s90, 0xa0000
	s_addc_u32 s99, s91, 0
	global_store_dwordx4 v240, v[12:15], s[98:99] offset:512
	global_store_dwordx4 v240, v[8:11], s[98:99] offset:528
	s_waitcnt vmcnt(14)
	v_pk_fma_f32 v[4:5], v[4:5], v[124:125], v[232:233]
	v_pk_fma_f32 v[6:7], v[6:7], v[126:127], v[234:235]
	v_pk_fma_f32 v[0:1], v[0:1], v[120:121], v[236:237]
	v_pk_fma_f32 v[2:3], v[2:3], v[122:123], v[238:239]
	s_add_u32 s98, s90, 0xb0000
	s_addc_u32 s99, s91, 0
	global_store_dwordx4 v240, v[4:7], s[98:99] offset:512
	global_store_dwordx4 v240, v[0:3], s[98:99] offset:528
	s_and_b64 vcc, exec, s[0:1]
	s_mov_b64 s[0:1], -1
	s_cbranch_vccnz .LBB0_1381
	s_andn2_b64 vcc, exec, s[6:7]
	s_cbranch_vccnz .LBB0_1380
	s_barrier
	s_branch .LBB0_1380

; __global__ void __launch_bounds__(512, 2) mega_fwd(Params p) {
	.amdhsa_kernel _Z8mega_fwd6Params
		.amdhsa_group_segment_fixed_size 0
		.amdhsa_private_segment_fixed_size 0
		.amdhsa_kernarg_size 504
		.amdhsa_user_sgpr_count 2
		.amdhsa_user_sgpr_dispatch_ptr 0
		.amdhsa_user_sgpr_queue_ptr 0
		.amdhsa_user_sgpr_kernarg_segment_ptr 1
		.amdhsa_user_sgpr_dispatch_id 0
		.amdhsa_user_sgpr_kernarg_preload_length 0
		.amdhsa_user_sgpr_kernarg_preload_offset 0
		.amdhsa_user_sgpr_private_segment_size 0
		.amdhsa_uses_dynamic_stack 0
		.amdhsa_enable_private_segment 0
		.amdhsa_system_sgpr_workgroup_id_x 1
		.amdhsa_system_sgpr_workgroup_id_y 0
		.amdhsa_system_sgpr_workgroup_id_z 0
		.amdhsa_system_sgpr_workgroup_info 0
		.amdhsa_system_vgpr_workitem_id 2
		.amdhsa_next_free_vgpr 245
		.amdhsa_next_free_sgpr 102
		.amdhsa_accum_offset 248
		.amdhsa_reserve_vcc 1
		.amdhsa_float_round_mode_32 0
		.amdhsa_float_round_mode_16_64 0
		.amdhsa_float_denorm_mode_32 3
		.amdhsa_float_denorm_mode_16_64 3
		.amdhsa_dx10_clamp 1
		.amdhsa_ieee_mode 1
		.amdhsa_fp16_overflow 0
		.amdhsa_tg_split 0
		.amdhsa_exception_fp_ieee_invalid_op 0
		.amdhsa_exception_fp_denorm_src 0
		.amdhsa_exception_fp_ieee_div_zero 0
		.amdhsa_exception_fp_ieee_overflow 0
		.amdhsa_exception_fp_ieee_underflow 0
		.amdhsa_exception_fp_ieee_inexact 0
		.amdhsa_exception_int_div_zero 0
	.end_amdhsa_kernel

; __global__ void __launch_bounds__(512, 2) mega_fwd(Params p) {
amdhsa.kernels:
  - .agpr_count:     0
    .args:
      - .offset:         0
        .size:           248
        .value_kind:     by_value
      - .offset:         248
        .size:           4
        .value_kind:     hidden_block_count_x
      - .offset:         252
        .size:           4
        .value_kind:     hidden_block_count_y
      - .offset:         256
        .size:           4
        .value_kind:     hidden_block_count_z
      - .offset:         260
        .size:           2
        .value_kind:     hidden_group_size_x
      - .offset:         262
        .size:           2
        .value_kind:     hidden_group_size_y
      - .offset:         264
        .size:           2
        .value_kind:     hidden_group_size_z
      - .offset:         266
        .size:           2
        .value_kind:     hidden_remainder_x
      - .offset:         268
        .size:           2
        .value_kind:     hidden_remainder_y
      - .offset:         270
        .size:           2
        .value_kind:     hidden_remainder_z
      - .offset:         288
        .size:           8
        .value_kind:     hidden_global_offset_x
      - .offset:         296
        .size:           8
        .value_kind:     hidden_global_offset_y
      - .offset:         304
        .size:           8
        .value_kind:     hidden_global_offset_z
      - .offset:         312
        .size:           2
        .value_kind:     hidden_grid_dims
      - .offset:         336
        .size:           8
        .value_kind:     hidden_multigrid_sync_arg
      - .offset:         368
        .size:           4
        .value_kind:     hidden_dynamic_lds_size
    .group_segment_fixed_size: 0
    .kernarg_segment_align: 8
    .kernarg_segment_size: 504
    .language:       OpenCL C
    .language_version:
      - 2
      - 0
    .max_flat_workgroup_size: 512
    .name:           _Z8mega_fwd6Params
    .private_segment_fixed_size: 0
    .sgpr_count:     108
    .sgpr_spill_count: 61
    .symbol:         _Z8mega_fwd6Params.kd
    .uniform_work_group_size: 1
    .uses_dynamic_stack: false
    .vgpr_count:     245
    .vgpr_spill_count: 0
    .wavefront_size: 64
